# in-proj epilogue: ssq atomics issued without draining earlier stores/atomics (8 serialized vmcnt(0) removed)
# speedup vs baseline: 1.0195x; 1.0195x over previous
; __device__ __forceinline__ u32x4 pack8(f32x4 a, f32x4 b) { u32x4 w; w.x = cvtpk(a[0], a[1]); w.y = cvtpk(a[2], a[3]); w.z = cvtpk(b[0], b[1]); w.w = cvtpk(b[2], b[3]); return w; }
; __device__ __forceinline__ float sumsq4(f32x4 x) { return (x[0] * x[0] + x[1] * x[1]) + (x[2] * x[2] + x[3] * x[3]); }
;     __device__ __forceinline__ void operator()(const AccT& acc, const Unit& u, int wr, int wc, int fr, int fq) const {
; #pragma unroll
;         for (int ai = 0; ai < 2; ++ai)
; #pragma unroll
;             for (int m = 0; m < 4; ++m) {
;                 const int row = EPI_ROW(u, ai, m);
; #pragma unroll
;                 for (int bj = 0; bj < 2; ++bj) *(u32x4*)(U + (size_t)row * LDU + EPI_COL(u, bj)) = pack8(acc[ai][bj][m][0], acc[ai][bj][m][1]);
;             }
;         if (u.pn >= 3) {
;             float* sp = u.pn == 3 ? ssq_q : ssq_kv; const float w1 = u.pn == 3 ? 1.f : 0.f;
; #pragma unroll
;             for (int ai = 0; ai < 2; ++ai)
; #pragma unroll
;                 for (int m = 0; m < 4; ++m) {
;                     float s = (sumsq4(acc[ai][0][m][0]) + sumsq4(acc[ai][0][m][1])) + w1 * (sumsq4(acc[ai][1][m][0]) + sumsq4(acc[ai][1][m][1]));
;                     s += __shfl_xor(s, 16); s += __shfl_xor(s, 32);
;                     if (fq == 0) unsafeAtomicAdd(sp + EPI_ROW(u, ai, m), s);
;                 }
.LBB0_885:
	v_mov_b32_e32 v141, v216
	s_lshl_b32 s2, s18, 8
	v_ashrrev_i32_e32 v140, 2, v141
	v_and_b32_e32 v140, 0xffffffc0, v140
	v_lshl_add_u32 v140, s20, 8, v140
	v_bfe_u32 v146, v141, 4, 2
	v_and_or_b32 v140, v141, 15, v140
	v_lshrrev_b32_e32 v141, 1, v141
	v_and_b32_e32 v141, 0x60, v141
	v_lshlrev_b32_e32 v144, 3, v146
	v_or3_b32 v144, v141, s2, v144
	v_readlane_b32 s2, v255, 2
	v_readlane_b32 s3, v255, 3
	v_ashrrev_i32_e32 v145, 31, v144
	v_lshlrev_b64 v[144:145], 1, v[144:145]
	v_mov_b64_e32 v[152:153], s[2:3]
	v_mad_i64_i32 v[154:155], s[2:3], v140, s61, v[152:153]
	v_cvt_pk_f16_f32 v148, v126, v127
	v_cvt_pk_f16_f32 v149, v128, v129
	v_cvt_pk_f16_f32 v150, v122, v123
	v_cvt_pk_f16_f32 v151, v124, v125
	v_lshl_add_u64 v[154:155], v[154:155], 0, v[144:145]
	flat_store_dwordx4 v[154:155], v[148:151]
	v_or_b32_e32 v141, 16, v140
	s_cmp_lt_i32 s18, 3
	v_cvt_pk_f16_f32 v148, v118, v119
	v_cvt_pk_f16_f32 v149, v120, v121
	v_cvt_pk_f16_f32 v150, v114, v115
	v_cvt_pk_f16_f32 v151, v116, v117
	flat_store_dwordx4 v[154:155], v[148:151] offset:256
	v_mad_i64_i32 v[154:155], s[2:3], v141, s61, v[152:153]
	s_nop 0
	v_cvt_pk_f16_f32 v148, v110, v111
	v_cvt_pk_f16_f32 v149, v112, v113
	v_cvt_pk_f16_f32 v150, v106, v107
	v_cvt_pk_f16_f32 v151, v108, v109
	v_lshl_add_u64 v[154:155], v[154:155], 0, v[144:145]
	flat_store_dwordx4 v[154:155], v[148:151]
	v_or_b32_e32 v141, 32, v140
	s_nop 0
	v_cvt_pk_f16_f32 v148, v102, v103
	v_cvt_pk_f16_f32 v149, v104, v105
	v_cvt_pk_f16_f32 v150, v98, v99
	v_cvt_pk_f16_f32 v151, v100, v101
	flat_store_dwordx4 v[154:155], v[148:151] offset:256
	v_mad_i64_i32 v[154:155], s[2:3], v141, s61, v[152:153]
	s_nop 0
	v_cvt_pk_f16_f32 v148, v94, v95
	v_cvt_pk_f16_f32 v149, v96, v97
	v_cvt_pk_f16_f32 v150, v90, v91
	v_cvt_pk_f16_f32 v151, v92, v93
	v_lshl_add_u64 v[154:155], v[154:155], 0, v[144:145]
	flat_store_dwordx4 v[154:155], v[148:151]
	v_or_b32_e32 v141, 48, v140
	s_nop 0
	v_cvt_pk_f16_f32 v148, v86, v87
	v_cvt_pk_f16_f32 v149, v88, v89
	v_cvt_pk_f16_f32 v150, v82, v83
	v_cvt_pk_f16_f32 v151, v84, v85
	flat_store_dwordx4 v[154:155], v[148:151] offset:256
	v_mad_i64_i32 v[154:155], s[2:3], v141, s61, v[152:153]
	s_nop 0
	v_cvt_pk_f16_f32 v148, v78, v79
	v_cvt_pk_f16_f32 v149, v80, v81
	v_cvt_pk_f16_f32 v150, v74, v75
	v_cvt_pk_f16_f32 v151, v76, v77
	v_lshl_add_u64 v[154:155], v[154:155], 0, v[144:145]
	flat_store_dwordx4 v[154:155], v[148:151]
	v_add_u32_e32 v141, 0x80, v140
	s_nop 0
	v_cvt_pk_f16_f32 v148, v70, v71
	v_cvt_pk_f16_f32 v149, v72, v73
	v_cvt_pk_f16_f32 v150, v66, v67
	v_cvt_pk_f16_f32 v151, v68, v69
	flat_store_dwordx4 v[154:155], v[148:151] offset:256
	v_mad_i64_i32 v[154:155], s[2:3], v141, s61, v[152:153]
	s_nop 0
	v_cvt_pk_f16_f32 v148, v62, v63
	v_cvt_pk_f16_f32 v149, v64, v65
	v_cvt_pk_f16_f32 v150, v58, v59
	v_cvt_pk_f16_f32 v151, v60, v61
	v_lshl_add_u64 v[154:155], v[154:155], 0, v[144:145]
	flat_store_dwordx4 v[154:155], v[148:151]
	v_add_u32_e32 v141, 0x90, v140
	s_nop 0
	v_cvt_pk_f16_f32 v148, v54, v55
	v_cvt_pk_f16_f32 v149, v56, v57
	v_cvt_pk_f16_f32 v150, v50, v51
	v_cvt_pk_f16_f32 v151, v52, v53
	flat_store_dwordx4 v[154:155], v[148:151] offset:256
	v_mad_i64_i32 v[154:155], s[2:3], v141, s61, v[152:153]
	s_nop 0
	v_cvt_pk_f16_f32 v148, v46, v47
	v_cvt_pk_f16_f32 v149, v48, v49
	v_cvt_pk_f16_f32 v150, v42, v43
	v_cvt_pk_f16_f32 v151, v44, v45
	v_lshl_add_u64 v[154:155], v[154:155], 0, v[144:145]
	flat_store_dwordx4 v[154:155], v[148:151]
	v_add_u32_e32 v141, 0xa0, v140
	s_nop 0
	v_cvt_pk_f16_f32 v148, v38, v39
	v_cvt_pk_f16_f32 v149, v40, v41
	v_cvt_pk_f16_f32 v150, v34, v35
	v_cvt_pk_f16_f32 v151, v36, v37
	flat_store_dwordx4 v[154:155], v[148:151] offset:256
	v_mad_i64_i32 v[154:155], s[2:3], v141, s61, v[152:153]
	s_nop 0
	v_cvt_pk_f16_f32 v148, v30, v31
	v_cvt_pk_f16_f32 v149, v32, v33
	v_cvt_pk_f16_f32 v150, v26, v27
	v_cvt_pk_f16_f32 v151, v28, v29
	v_lshl_add_u64 v[154:155], v[154:155], 0, v[144:145]
	v_add_u32_e32 v141, 0xb0, v140
	flat_store_dwordx4 v[154:155], v[148:151]
	v_mad_i64_i32 v[152:153], s[2:3], v141, s61, v[152:153]
	s_nop 0
	v_cvt_pk_f16_f32 v148, v22, v23
	v_cvt_pk_f16_f32 v149, v24, v25
	v_cvt_pk_f16_f32 v150, v18, v19
	v_cvt_pk_f16_f32 v151, v20, v21
	flat_store_dwordx4 v[154:155], v[148:151] offset:256
	v_lshl_add_u64 v[144:145], v[152:153], 0, v[144:145]
	s_nop 0
	v_cvt_pk_f16_f32 v148, v14, v15
	v_cvt_pk_f16_f32 v149, v16, v17
	v_cvt_pk_f16_f32 v150, v10, v11
	v_cvt_pk_f16_f32 v151, v12, v13
	flat_store_dwordx4 v[144:145], v[148:151]
	s_nop 1
	v_cvt_pk_f16_f32 v148, v6, v7
	v_cvt_pk_f16_f32 v149, v8, v9
	v_cvt_pk_f16_f32 v150, v2, v3
	v_cvt_pk_f16_f32 v151, v4, v5
	flat_store_dwordx4 v[144:145], v[148:151] offset:256
	s_cbranch_scc1 .LBB0_903
	v_mul_f32_e32 v127, v127, v127
	v_mul_f32_e32 v123, v123, v123
	v_mul_f32_e32 v119, v119, v119
	v_mul_f32_e32 v115, v115, v115
	v_and_b32_e32 v147, 64, v237
	v_fmac_f32_e32 v127, v126, v126
	v_mul_f32_e32 v126, v129, v129
	v_fmac_f32_e32 v123, v122, v122
	v_mul_f32_e32 v122, v125, v125
	v_fmac_f32_e32 v119, v118, v118
	v_mul_f32_e32 v118, v121, v121
	v_fmac_f32_e32 v115, v114, v114
	v_mul_f32_e32 v114, v117, v117
	s_cmp_eq_u32 s18, 3
	v_xor_b32_e32 v145, 16, v237
	v_add_u32_e32 v147, 64, v147
	v_fmac_f32_e32 v126, v128, v128
	v_fmac_f32_e32 v122, v124, v124
	v_fmac_f32_e32 v118, v120, v120
	v_fmac_f32_e32 v114, v116, v116
	s_cselect_b64 s[2:3], -1, 0
	v_cmp_lt_i32_e32 vcc, v145, v147
	v_add_f32_e32 v126, v127, v126
	v_add_f32_e32 v122, v123, v122
	v_add_f32_e32 v118, v119, v118
	v_add_f32_e32 v114, v115, v114
	v_cndmask_b32_e64 v144, 0, 1.0, s[2:3]
	v_cndmask_b32_e32 v145, v237, v145, vcc
	v_add_f32_e32 v122, v122, v126
	v_add_f32_e32 v114, v114, v118
	v_lshlrev_b32_e32 v145, 2, v145
	v_fmac_f32_e32 v122, v144, v114
	ds_bpermute_b32 v114, v145, v122
	v_xor_b32_e32 v115, 32, v237
	v_cmp_lt_i32_e32 vcc, v115, v147
	s_and_b64 s[2:3], s[2:3], exec
	v_readlane_b32 s2, v255, 8
	v_cndmask_b32_e32 v115, v237, v115, vcc
	v_lshlrev_b32_e32 v116, 2, v115
	s_waitcnt lgkmcnt(0)
	v_add_f32_e32 v117, v122, v114
	ds_bpermute_b32 v118, v116, v117
	v_readlane_b32 s3, v255, 9
	v_ashrrev_i32_e32 v141, 31, v140
	s_cselect_b32 s3, s3, s39
	s_cselect_b32 s2, s2, s38
	v_cmp_eq_u32_e32 vcc, 0, v146
	v_lshl_add_u64 v[114:115], v[140:141], 2, s[2:3]
	s_and_saveexec_b64 s[18:19], vcc
	s_cbranch_execz .LBB0_888
	s_waitcnt lgkmcnt(0)
	v_add_f32_e32 v117, v117, v118
	flat_atomic_add_f32 v[114:115], v117
; __device__ __forceinline__ float sumsq4(f32x4 x) { return (x[0] * x[0] + x[1] * x[1]) + (x[2] * x[2] + x[3] * x[3]); }
;     __device__ __forceinline__ void operator()(const AccT& acc, const Unit& u, int wr, int wc, int fr, int fq) const {
;     ...
;         if (u.pn >= 3) {
;             float* sp = u.pn == 3 ? ssq_q : ssq_kv; const float w1 = u.pn == 3 ? 1.f : 0.f;
; #pragma unroll
;             for (int ai = 0; ai < 2; ++ai)
; #pragma unroll
;                 for (int m = 0; m < 4; ++m) {
;                     float s = (sumsq4(acc[ai][0][m][0]) + sumsq4(acc[ai][0][m][1])) + w1 * (sumsq4(acc[ai][1][m][0]) + sumsq4(acc[ai][1][m][1]));
;                     s += __shfl_xor(s, 16); s += __shfl_xor(s, 32);
;                     if (fq == 0) unsafeAtomicAdd(sp + EPI_ROW(u, ai, m), s);
;                 }
.LBB0_888:
	s_or_b64 exec, exec, s[18:19]
	v_mul_f32_e32 v111, v111, v111
	v_mul_f32_e32 v107, v107, v107
	v_mul_f32_e32 v103, v103, v103
	v_mul_f32_e32 v99, v99, v99
	v_fmac_f32_e32 v111, v110, v110
	v_mul_f32_e32 v110, v113, v113
	v_fmac_f32_e32 v107, v106, v106
	v_mul_f32_e32 v106, v109, v109
	v_fmac_f32_e32 v103, v102, v102
	v_mul_f32_e32 v102, v105, v105
	v_fmac_f32_e32 v99, v98, v98
	v_mul_f32_e32 v98, v101, v101
	v_fmac_f32_e32 v110, v112, v112
	v_fmac_f32_e32 v106, v108, v108
	v_fmac_f32_e32 v102, v104, v104
	v_fmac_f32_e32 v98, v100, v100
	v_add_f32_e32 v110, v111, v110
	v_add_f32_e32 v106, v107, v106
	v_add_f32_e32 v102, v103, v102
	v_add_f32_e32 v98, v99, v98
	v_add_f32_e32 v106, v106, v110
	v_add_f32_e32 v98, v98, v102
	v_fmac_f32_e32 v106, v144, v98
	ds_bpermute_b32 v98, v145, v106
	s_waitcnt lgkmcnt(0)
	v_add_f32_e32 v98, v106, v98
	ds_bpermute_b32 v99, v116, v98
	s_and_saveexec_b64 s[18:19], vcc
	s_cbranch_execz .LBB0_890
	s_waitcnt lgkmcnt(0)
	v_add_f32_e32 v98, v98, v99
	flat_atomic_add_f32 v[114:115], v98 offset:64
.LBB0_890:
	s_or_b64 exec, exec, s[18:19]
	v_mul_f32_e32 v95, v95, v95
	v_mul_f32_e32 v91, v91, v91
	v_mul_f32_e32 v87, v87, v87
	v_mul_f32_e32 v83, v83, v83
	v_fmac_f32_e32 v95, v94, v94
	v_mul_f32_e32 v94, v97, v97
	v_fmac_f32_e32 v91, v90, v90
	v_mul_f32_e32 v90, v93, v93
	v_fmac_f32_e32 v87, v86, v86
	v_mul_f32_e32 v86, v89, v89
	v_fmac_f32_e32 v83, v82, v82
	v_mul_f32_e32 v82, v85, v85
	v_fmac_f32_e32 v94, v96, v96
	v_fmac_f32_e32 v90, v92, v92
	v_fmac_f32_e32 v86, v88, v88
	v_fmac_f32_e32 v82, v84, v84
	v_add_f32_e32 v94, v95, v94
	v_add_f32_e32 v90, v91, v90
	v_add_f32_e32 v86, v87, v86
	v_add_f32_e32 v82, v83, v82
	v_add_f32_e32 v90, v90, v94
	v_add_f32_e32 v82, v82, v86
	v_fmac_f32_e32 v90, v144, v82
	ds_bpermute_b32 v82, v145, v90
	s_waitcnt lgkmcnt(0)
	v_add_f32_e32 v82, v90, v82
	ds_bpermute_b32 v83, v116, v82
	s_and_saveexec_b64 s[18:19], vcc
	s_cbranch_execz .LBB0_892
	s_waitcnt lgkmcnt(0)
	v_add_f32_e32 v82, v82, v83
	flat_atomic_add_f32 v[114:115], v82 offset:128
.LBB0_892:
	s_or_b64 exec, exec, s[18:19]
	v_mul_f32_e32 v79, v79, v79
	v_mul_f32_e32 v75, v75, v75
	v_mul_f32_e32 v71, v71, v71
	v_mul_f32_e32 v67, v67, v67
	v_fmac_f32_e32 v79, v78, v78
	v_mul_f32_e32 v78, v81, v81
	v_fmac_f32_e32 v75, v74, v74
	v_mul_f32_e32 v74, v77, v77
	v_fmac_f32_e32 v71, v70, v70
	v_mul_f32_e32 v70, v73, v73
	v_fmac_f32_e32 v67, v66, v66
	v_mul_f32_e32 v66, v69, v69
	v_fmac_f32_e32 v78, v80, v80
	v_fmac_f32_e32 v74, v76, v76
	v_fmac_f32_e32 v70, v72, v72
	v_fmac_f32_e32 v66, v68, v68
	v_add_f32_e32 v78, v79, v78
	v_add_f32_e32 v74, v75, v74
	v_add_f32_e32 v70, v71, v70
	v_add_f32_e32 v66, v67, v66
	v_add_f32_e32 v74, v74, v78
	v_add_f32_e32 v66, v66, v70
	v_fmac_f32_e32 v74, v144, v66
	ds_bpermute_b32 v66, v145, v74
	s_waitcnt lgkmcnt(0)
	v_add_f32_e32 v66, v74, v66
	ds_bpermute_b32 v67, v116, v66
	s_and_saveexec_b64 s[18:19], vcc
	s_cbranch_execz .LBB0_894
	s_waitcnt lgkmcnt(0)
	v_add_f32_e32 v66, v66, v67
	flat_atomic_add_f32 v[114:115], v66 offset:192
.LBB0_894:
	s_or_b64 exec, exec, s[18:19]
	v_mul_f32_e32 v63, v63, v63
	v_mul_f32_e32 v59, v59, v59
	v_mul_f32_e32 v55, v55, v55
	v_mul_f32_e32 v51, v51, v51
	v_fmac_f32_e32 v63, v62, v62
	v_mul_f32_e32 v62, v65, v65
	v_fmac_f32_e32 v59, v58, v58
	v_mul_f32_e32 v58, v61, v61
	v_fmac_f32_e32 v55, v54, v54
	v_mul_f32_e32 v54, v57, v57
	v_fmac_f32_e32 v51, v50, v50
	v_mul_f32_e32 v50, v53, v53
	v_fmac_f32_e32 v62, v64, v64
	v_fmac_f32_e32 v58, v60, v60
	v_fmac_f32_e32 v54, v56, v56
	v_fmac_f32_e32 v50, v52, v52
	v_add_f32_e32 v62, v63, v62
	v_add_f32_e32 v58, v59, v58
	v_add_f32_e32 v54, v55, v54
	v_add_f32_e32 v50, v51, v50
	v_add_f32_e32 v58, v58, v62
	v_add_f32_e32 v50, v50, v54
	v_fmac_f32_e32 v58, v144, v50
	ds_bpermute_b32 v50, v145, v58
	s_waitcnt lgkmcnt(0)
	v_add_f32_e32 v50, v58, v50
	ds_bpermute_b32 v51, v116, v50
	s_and_saveexec_b64 s[18:19], vcc
	s_cbranch_execz .LBB0_896
	s_waitcnt lgkmcnt(0)
	v_add_f32_e32 v50, v50, v51
	flat_atomic_add_f32 v[114:115], v50 offset:512
.LBB0_896:
	s_or_b64 exec, exec, s[18:19]
	v_mul_f32_e32 v47, v47, v47
	v_mul_f32_e32 v43, v43, v43
	v_mul_f32_e32 v39, v39, v39
	v_mul_f32_e32 v35, v35, v35
	v_fmac_f32_e32 v47, v46, v46
	v_mul_f32_e32 v46, v49, v49
	v_fmac_f32_e32 v43, v42, v42
	v_mul_f32_e32 v42, v45, v45
	v_fmac_f32_e32 v39, v38, v38
	v_mul_f32_e32 v38, v41, v41
	v_fmac_f32_e32 v35, v34, v34
	v_mul_f32_e32 v34, v37, v37
	v_fmac_f32_e32 v46, v48, v48
	v_fmac_f32_e32 v42, v44, v44
	v_fmac_f32_e32 v38, v40, v40
	v_fmac_f32_e32 v34, v36, v36
	v_add_f32_e32 v46, v47, v46
	v_add_f32_e32 v42, v43, v42
	v_add_f32_e32 v38, v39, v38
	v_add_f32_e32 v34, v35, v34
	v_add_f32_e32 v42, v42, v46
	v_add_f32_e32 v34, v34, v38
	v_fmac_f32_e32 v42, v144, v34
	ds_bpermute_b32 v34, v145, v42
	s_waitcnt lgkmcnt(0)
	v_add_f32_e32 v34, v42, v34
	ds_bpermute_b32 v35, v116, v34
	s_and_saveexec_b64 s[18:19], vcc
	s_cbranch_execz .LBB0_898
	s_waitcnt lgkmcnt(0)
	v_add_f32_e32 v34, v34, v35
	flat_atomic_add_f32 v[114:115], v34 offset:576
.LBB0_898:
	s_or_b64 exec, exec, s[18:19]
	v_mul_f32_e32 v31, v31, v31
	v_mul_f32_e32 v27, v27, v27
	v_mul_f32_e32 v23, v23, v23
	v_mul_f32_e32 v19, v19, v19
	v_fmac_f32_e32 v31, v30, v30
	v_mul_f32_e32 v30, v33, v33
	v_fmac_f32_e32 v27, v26, v26
	v_mul_f32_e32 v26, v29, v29
	v_fmac_f32_e32 v23, v22, v22
	v_mul_f32_e32 v22, v25, v25
	v_fmac_f32_e32 v19, v18, v18
	v_mul_f32_e32 v18, v21, v21
	v_fmac_f32_e32 v30, v32, v32
	v_fmac_f32_e32 v26, v28, v28
	v_fmac_f32_e32 v22, v24, v24
	v_fmac_f32_e32 v18, v20, v20
	v_add_f32_e32 v30, v31, v30
	v_add_f32_e32 v26, v27, v26
	v_add_f32_e32 v22, v23, v22
	v_add_f32_e32 v18, v19, v18
	v_add_f32_e32 v26, v26, v30
	v_add_f32_e32 v18, v18, v22
	v_fmac_f32_e32 v26, v144, v18
	ds_bpermute_b32 v18, v145, v26
	s_waitcnt lgkmcnt(0)
	v_add_f32_e32 v18, v26, v18
	ds_bpermute_b32 v19, v116, v18
	s_and_saveexec_b64 s[18:19], vcc
	s_cbranch_execz .LBB0_900
	s_waitcnt lgkmcnt(0)
	v_add_f32_e32 v18, v18, v19
	flat_atomic_add_f32 v[114:115], v18 offset:640
.LBB0_900:
	s_or_b64 exec, exec, s[18:19]
	v_mul_f32_e32 v15, v15, v15
	v_mul_f32_e32 v11, v11, v11
	v_mul_f32_e32 v7, v7, v7
	v_mul_f32_e32 v3, v3, v3
	v_fmac_f32_e32 v15, v14, v14
	v_mul_f32_e32 v14, v17, v17
	v_fmac_f32_e32 v11, v10, v10
	v_mul_f32_e32 v10, v13, v13
	v_fmac_f32_e32 v7, v6, v6
	v_mul_f32_e32 v6, v9, v9
	v_fmac_f32_e32 v3, v2, v2
	v_mul_f32_e32 v2, v5, v5
	v_fmac_f32_e32 v14, v16, v16
	v_fmac_f32_e32 v10, v12, v12
	v_fmac_f32_e32 v6, v8, v8
	v_fmac_f32_e32 v2, v4, v4
	v_add_f32_e32 v14, v15, v14
	v_add_f32_e32 v10, v11, v10
	v_add_f32_e32 v6, v7, v6
	v_add_f32_e32 v2, v3, v2
	v_add_f32_e32 v10, v10, v14
	v_add_f32_e32 v2, v2, v6
	v_fmac_f32_e32 v10, v144, v2
	ds_bpermute_b32 v2, v145, v10
	s_waitcnt lgkmcnt(0)
	v_add_f32_e32 v2, v10, v2
	ds_bpermute_b32 v3, v116, v2
	s_and_saveexec_b64 s[18:19], vcc
	s_cbranch_execz .LBB0_902
	s_waitcnt lgkmcnt(0)
	v_add_f32_e32 v2, v2, v3
	flat_atomic_add_f32 v[114:115], v2 offset:704
